# code placement: one s_nop at entry shifts the code by 4 bytes so the three GEMM K-loop heads are 8-byte aligned again (as in the baseline)
# baseline (speedup 1.0000x reference)
_Z10fwd_kernel6Params:
	s_mov_b64 s[94:95], s[0:1]
	s_mov_b32 s100, 0
	s_mov_b32 s101, 0
	s_nop 0
	s_load_dwordx4 s[44:47], s[0:1], 0xc8
	s_load_dword s48, s[0:1], 0xd8
	s_add_u32 s0, s94, 0xd8
	s_addc_u32 s1, s95, 0
	v_readfirstlane_b32 s33, v0
	v_writelane_b32 v251, s0, 0
	v_cmp_gt_u32_e32 vcc, 64, v0
	s_nop 0
	v_writelane_b32 v251, s1, 1
	s_and_saveexec_b64 s[0:1], vcc
	v_lshl_add_u32 v1, v0, 2, 0
	v_add_u32_e32 v1, 0x27c00, v1
	v_mov_b32_e32 v2, 0
	ds_write_b32 v1, v2
	s_or_b64 exec, exec, s[0:1]
	s_waitcnt lgkmcnt(0)
	s_barrier
	s_getreg_b32 s3, hwreg(HW_REG_XCC_ID, 0, 4)
	s_mov_b32 s11, 0
	v_cmp_eq_u32_e32 vcc, 0, v0
	s_and_saveexec_b64 s[0:1], vcc
	s_cbranch_execz .LBB0_5
	s_mov_b64 s[4:5], exec
	v_mbcnt_lo_u32_b32 v0, s4, 0
	v_mbcnt_hi_u32_b32 v0, s5, v0
	v_cmp_eq_u32_e32 vcc, 0, v0
	s_and_b64 s[6:7], exec, vcc
	s_mov_b64 exec, s[6:7]
	s_cbranch_execz .LBB0_5
	s_lshl_b32 s3, s3, 8
	s_and_b32 s3, s3, 0xf00
	s_bcnt1_i32_b64 s4, s[4:5]
	v_mov_b32_e32 v0, s3
	v_mov_b32_e32 v1, s4
	global_atomic_add v0, v1, s[46:47] offset:1024
	s_lshr_b32 s6, s3, 8
	s_and_b32 s7, s2, 7
	s_cmp_eq_u32 s6, s7
	s_cbranch_scc1 .LBB0_5
	v_mov_b32_e32 v0, 0x280
	global_atomic_add v0, v1, s[46:47]
